# attention unit epilogue: 8-byte row pieces paired across lane halves (v_permlane32_swap) and stored as four 16-byte stores instead of eight 8-byte stores
# baseline (speedup 1.0000x reference)
.Lpipe_nofetch:
	s_add_u32 s2, s78, s8
	s_addc_u32 s3, s79, s9
	v_ashrrev_i32_e32 v173, 31, v172
	v_lshl_add_u64 v[2:3], v[172:173], 2, s[2:3]
	v_mov_b32_e32 v0, v175
	global_load_dwordx4 v[94:97], v[2:3], off
	global_load_dwordx4 v[90:93], v[2:3], off offset:32
	global_load_dwordx4 v[86:89], v[2:3], off offset:64
	global_load_dwordx4 v[82:85], v[2:3], off offset:96
	global_load_dwordx4 v[14:17], v[2:3], off offset:128
	global_load_dwordx4 v[10:13], v[2:3], off offset:160
	global_load_dwordx4 v[6:9], v[2:3], off offset:192
	s_nop 0
	global_load_dwordx4 v[2:5], v[2:3], off offset:224
	v_mov_b32_e32 v147, 0
	s_cmpk_gt_i32 s46, 0x4f
	v_readlane_b32 s2, v245, 13
	s_cselect_b32 s2, s2, 0
	s_sub_i32 s2, s46, s2
	s_bfe_u32 s4, s2, 0x30001
	s_and_b32 s3, s2, 1
	s_xor_b32 s5, s4, 7
	s_or_b32 s4, s4, 8
	s_cmp_eq_u32 s3, 0
	s_cselect_b32 s3, s4, s5
	s_mov_b64 s[4:5], s[0:1]
	s_mov_b64 s[12:13], s[0:1]
	s_load_dwordx2 s[4:5], s[4:5], 0x80
	s_mov_b64 s[12:13], s[0:1]
	s_ashr_i32 s2, s2, 4
	s_sub_i32 s12, 8, s2
	v_cvt_f32_i32_e32 v146, s12
	v_mov_b32_e32 v156, v220
	v_readlane_b32 s13, v245, 17
	v_exp_f32_e64 v146, -v146
	s_sub_i32 s55, 7, s2
	s_lshl_b32 s55, s55, 6
	v_ashrrev_i32_e32 v148, 5, v156
	v_readfirstlane_b32 s12, v146
	v_ashrrev_i32_e32 v146, 3, v156
	v_add_u32_e32 v146, s13, v146
	v_mul_lo_u32 v149, v146, s88
	v_lshrrev_b32_e32 v146, 1, v146
	s_add_i32 s13, s55, 0x200
	v_xor_b32_e32 v146, v146, v156
	v_add_u32_e32 v149, s13, v149
	v_lshlrev_b32_e32 v146, 3, v146
	v_readlane_b32 s13, v245, 16
	v_and_or_b32 v146, v146, 56, v149
	v_lshlrev_b32_e32 v150, 3, v156
	v_lshl_add_u32 v149, v148, 3, s13
	v_readlane_b32 s13, v245, 18
	s_add_i32 s13, s13, s55
	v_and_b32_e32 v157, 24, v150
	v_or_b32_e32 v155, s13, v157
	v_readlane_b32 s13, v245, 19
	s_waitcnt lgkmcnt(0)
	s_add_u32 s4, s4, s13
	s_addc_u32 s5, s5, 0
	s_add_u32 s60, s4, 0x13200000
	s_addc_u32 s61, s5, 0
	s_mul_i32 s4, s3, 0xc0000
	s_add_u32 s80, s60, s4
	v_lshlrev_b32_e32 v146, 1, v146
	s_addc_u32 s81, s61, 0
	s_movk_i32 s4, 0xfc00
	v_lshl_add_u64 v[150:151], s[80:81], 0, v[146:147]
	s_mov_b32 s5, -1
	v_lshl_add_u64 v[152:153], v[150:151], 0, s[4:5]
	v_readlane_b32 s5, v245, 22
	s_mov_b32 s4, m0
	s_mov_b32 m0, s5
	s_nop 0
	global_load_lds_dwordx4 v[152:153], off
	s_mov_b32 m0, s4
	s_mov_b64 s[4:5], 0x2fc00
	v_bfe_u32 v154, v156, 2, 3
	v_lshl_add_u64 v[152:153], v[150:151], 0, s[4:5]
	v_readlane_b32 s5, v245, 20
	s_mov_b32 s4, m0
	s_mov_b32 m0, s5
	s_nop 0
	global_load_lds_dwordx4 v[152:153], off
	s_mov_b32 m0, s4
	s_mov_b64 s[4:5], 0x5fc00
	v_or_b32_e32 v149, v149, v154
	v_lshl_add_u64 v[152:153], v[150:151], 0, s[4:5]
	v_readlane_b32 s5, v245, 21
	s_mov_b32 s4, m0
	s_mov_b32 m0, s5
	s_nop 0
	global_load_lds_dwordx4 v[152:153], off
	s_mov_b32 m0, s4
	s_mov_b64 s[4:5], 0x8fc00
	v_mul_lo_u32 v149, v149, s88
	v_lshl_add_u64 v[152:153], v[150:151], 0, s[4:5]
	v_readlane_b32 s5, v245, 23
	s_mov_b32 s4, m0
	s_mov_b32 m0, s5
	s_nop 0
	global_load_lds_dwordx4 v[152:153], off
	s_mov_b32 m0, s4
	v_add_lshl_u32 v170, v155, v149, 1
	s_mov_b32 s4, m0
	s_mov_b32 m0, s64
	s_nop 0
	global_load_lds_dwordx4 v[150:151], off
	s_mov_b32 m0, s4
	v_mov_b32_e32 v171, v1
	v_lshl_add_u64 v[150:151], s[80:81], 0, v[170:171]
	v_readlane_b32 s5, v245, 24
	s_mov_b32 s4, m0
	s_mov_b32 m0, s5
	s_nop 0
	global_load_lds_dwordx4 v[150:151], off
	s_mov_b32 m0, s4
	v_lshlrev_b32_e32 v150, 2, v156
	v_readlane_b32 s4, v245, 25
	v_and_b32_e32 v155, 4, v150
	v_bitop3_b32 v150, v150, v154, 4 bitop3:0x6c
	v_lshl_add_u32 v149, v156, 6, s4
	v_and_b32_e32 v149, 0xffffff80, v149
	v_add_u32_e32 v149, s63, v149
	v_lshl_add_u32 v150, v150, 4, v149
	s_ashr_i32 s101, s2, 31
	s_mov_b32 s100, s2
	s_lshl_b64 s[100:101], s[100:101], 2
	s_sub_u32 s100, s7, s100
	s_subb_u32 s101, s33, s101
	v_mov_b32_e32 v248, 0
	global_load_dword v249, v248, s[100:101] offset:28 sc1
	s_add_u32 s100, s80, 0x30000
	s_addc_u32 s101, s81, 0
	v_lshl_add_u64 v[250:251], s[100:101], 0, v[146:147]
	v_lshl_add_u64 v[252:253], s[100:101], 0, v[170:171]
	v_readlane_b32 s98, v245, 27
	s_mov_b32 s99, m0
	s_mov_b32 m0, s98
	s_nop 0
	global_load_lds_dwordx4 v[250:251], off
	v_readlane_b32 s98, v245, 28
	s_nop 0
	s_mov_b32 m0, s98
	s_nop 0
	global_load_lds_dwordx4 v[252:253], off
	s_add_u32 s100, s80, 0x60000
	s_addc_u32 s101, s81, 0
	v_lshl_add_u64 v[250:251], s[100:101], 0, v[146:147]
	v_lshl_add_u64 v[252:253], s[100:101], 0, v[170:171]
	v_readlane_b32 s98, v245, 29
	s_nop 0
	s_mov_b32 m0, s98
	s_nop 0
	global_load_lds_dwordx4 v[250:251], off
	v_readlane_b32 s98, v245, 30
	s_nop 0
	s_mov_b32 m0, s98
	s_nop 0
	global_load_lds_dwordx4 v[252:253], off
	s_mov_b32 m0, s99
	s_mov_b32 s4, s2
	s_mov_b32 s5, s3
	s_ashr_i32 s77, s76, 31
	v_permlane32_swap_b32_e32 v175, v0
	s_nop 0
	v_add_f32_e32 v0, v175, v0
	v_div_scale_f32 v98, s[2:3], v0, v0, 1.0
	v_rcp_f32_e32 v99, v98
	s_nop 0
	v_fma_f32 v100, -v98, v99, 1.0
	v_fmac_f32_e32 v99, v100, v99
	v_div_scale_f32 v100, vcc, 1.0, v0, 1.0
	v_mul_f32_e32 v101, v100, v99
	v_fma_f32 v102, -v98, v101, v100
	v_fmac_f32_e32 v101, v102, v99
	v_fma_f32 v98, -v98, v101, v100
	v_div_fmas_f32 v98, v98, v99, v101
	v_div_fixup_f32 v0, v98, v0, 1.0
	v_mov_b32_e32 v98, v174
	s_nop 1
	v_permlane32_swap_b32_e32 v174, v98
	s_nop 0
	v_add_f32_e32 v98, v174, v98
	v_div_scale_f32 v99, s[2:3], v98, v98, 1.0
	v_rcp_f32_e32 v100, v99
	s_mov_b32 s2, 0xf800000
	v_fma_f32 v101, -v99, v100, 1.0
	v_fmac_f32_e32 v100, v101, v100
	v_div_scale_f32 v101, vcc, 1.0, v98, 1.0
	v_mul_f32_e32 v102, v101, v100
	v_fma_f32 v103, -v99, v102, v101
	v_fmac_f32_e32 v102, v103, v100
	v_fma_f32 v99, -v99, v102, v101
	v_div_fmas_f32 v99, v99, v100, v102
	v_div_fixup_f32 v98, v99, v98, 1.0
	v_mul_f32_e32 v98, v183, v98
	v_mul_f32_e32 v66, v66, v98
	v_fma_f32 v50, v50, v0, -v66
	v_mul_f32_e32 v66, v67, v98
	v_fma_f32 v51, v51, v0, -v66
	v_mul_f32_e32 v66, v51, v51
	v_mul_f32_e32 v67, v68, v98
	v_fmac_f32_e32 v66, v50, v50
	v_fma_f32 v52, v52, v0, -v67
	v_mul_f32_e32 v67, v69, v98
	v_fmac_f32_e32 v66, v52, v52
	v_fma_f32 v53, v53, v0, -v67
	v_mul_f32_e32 v67, v70, v98
	v_fmac_f32_e32 v66, v53, v53
	v_fma_f32 v54, v54, v0, -v67
	v_mul_f32_e32 v67, v71, v98
	v_fmac_f32_e32 v66, v54, v54
	v_fma_f32 v55, v55, v0, -v67
	v_mul_f32_e32 v67, v72, v98
	v_fmac_f32_e32 v66, v55, v55
	v_fma_f32 v56, v56, v0, -v67
	v_mul_f32_e32 v67, v73, v98
	v_fmac_f32_e32 v66, v56, v56
	v_fma_f32 v57, v57, v0, -v67
	v_mul_f32_e32 v67, v74, v98
	v_fmac_f32_e32 v66, v57, v57
	v_fma_f32 v58, v58, v0, -v67
	v_mul_f32_e32 v67, v75, v98
	v_fmac_f32_e32 v66, v58, v58
	v_fma_f32 v59, v59, v0, -v67
	v_mul_f32_e32 v67, v76, v98
	v_fmac_f32_e32 v66, v59, v59
	v_fma_f32 v60, v60, v0, -v67
	v_mul_f32_e32 v67, v77, v98
	v_fmac_f32_e32 v66, v60, v60
	v_fma_f32 v61, v61, v0, -v67
	v_mul_f32_e32 v67, v78, v98
	v_fmac_f32_e32 v66, v61, v61
	v_fma_f32 v62, v62, v0, -v67
	v_mul_f32_e32 v67, v79, v98
	v_fmac_f32_e32 v66, v62, v62
	v_fma_f32 v63, v63, v0, -v67
	v_mul_f32_e32 v67, v80, v98
	v_fmac_f32_e32 v66, v63, v63
	v_fma_f32 v64, v64, v0, -v67
	v_mul_f32_e32 v67, v81, v98
	v_fmac_f32_e32 v66, v64, v64
	v_fma_f32 v65, v65, v0, -v67
	v_mul_f32_e32 v34, v34, v98
	v_fmac_f32_e32 v66, v65, v65
	v_fma_f32 v34, v18, v0, -v34
	v_mul_f32_e32 v18, v35, v98
	v_fmac_f32_e32 v66, v34, v34
	v_fma_f32 v35, v19, v0, -v18
	v_mul_f32_e32 v18, v36, v98
	v_fmac_f32_e32 v66, v35, v35
	v_fma_f32 v36, v20, v0, -v18
	v_mul_f32_e32 v18, v37, v98
	v_fmac_f32_e32 v66, v36, v36
	v_fma_f32 v37, v21, v0, -v18
	v_mul_f32_e32 v18, v38, v98
	v_fmac_f32_e32 v66, v37, v37
	v_fma_f32 v38, v22, v0, -v18
	v_mul_f32_e32 v18, v39, v98
	v_fmac_f32_e32 v66, v38, v38
	v_fma_f32 v39, v23, v0, -v18
	v_mul_f32_e32 v18, v40, v98
	v_fmac_f32_e32 v66, v39, v39
	v_fma_f32 v24, v24, v0, -v18
	v_mul_f32_e32 v18, v41, v98
	v_fmac_f32_e32 v66, v24, v24
	v_fma_f32 v25, v25, v0, -v18
	v_mul_f32_e32 v18, v42, v98
	v_fmac_f32_e32 v66, v25, v25
	v_fma_f32 v26, v26, v0, -v18
	v_mul_f32_e32 v18, v43, v98
	v_fmac_f32_e32 v66, v26, v26
	v_fma_f32 v27, v27, v0, -v18
	v_mul_f32_e32 v18, v44, v98
	v_fmac_f32_e32 v66, v27, v27
	v_fma_f32 v28, v28, v0, -v18
	v_mul_f32_e32 v18, v45, v98
	v_fmac_f32_e32 v66, v28, v28
	v_fma_f32 v29, v29, v0, -v18
	v_mul_f32_e32 v18, v46, v98
	v_fmac_f32_e32 v66, v29, v29
	v_fma_f32 v30, v30, v0, -v18
	v_mul_f32_e32 v18, v47, v98
	v_fmac_f32_e32 v66, v30, v30
	v_fma_f32 v31, v31, v0, -v18
	v_mul_f32_e32 v18, v48, v98
	v_fmac_f32_e32 v66, v31, v31
	v_fma_f32 v32, v32, v0, -v18
	v_mul_f32_e32 v18, v49, v98
	v_fmac_f32_e32 v66, v32, v32
	v_fma_f32 v33, v33, v0, -v18
	v_fmac_f32_e32 v66, v33, v33
	v_mov_b32_e32 v0, v66
	s_nop 1
	v_permlane32_swap_b32_e32 v66, v0
	s_nop 0
	v_add_f32_e32 v0, v66, v0
	v_fmamk_f32 v0, v0, 0x3c800000, v233
	v_cmp_gt_f32_e32 vcc, s2, v0
	v_mul_f32_e32 v18, 0x4f800000, v0
	s_nop 0
	v_cndmask_b32_e32 v0, v0, v18, vcc
	v_sqrt_f32_e32 v18, v0
	s_nop 0
	v_add_u32_e32 v19, -1, v18
	v_fma_f32 v20, -v19, v18, v0
	v_cmp_ge_f32_e64 s[2:3], 0, v20
	v_add_u32_e32 v20, 1, v18
	s_nop 0
	v_cndmask_b32_e64 v19, v18, v19, s[2:3]
	v_fma_f32 v18, -v20, v18, v0
	v_cmp_lt_f32_e64 s[2:3], 0, v18
	s_nop 1
	v_cndmask_b32_e64 v18, v19, v20, s[2:3]
	v_mul_f32_e32 v19, 0x37800000, v18
	v_cndmask_b32_e32 v18, v18, v19, vcc
	v_cmp_class_f32_e32 vcc, v0, v232
	s_nop 1
	v_cndmask_b32_e32 v0, v18, v0, vcc
	v_div_scale_f32 v18, s[2:3], v0, v0, v177
	v_rcp_f32_e32 v19, v18
	v_readlane_b32 s2, v244, 1
	s_add_i32 s2, s2, s68
	v_fma_f32 v20, -v18, v19, 1.0
	v_fmac_f32_e32 v19, v20, v19
	v_div_scale_f32 v20, vcc, v177, v0, v177
	v_mul_f32_e32 v21, v20, v19
	v_fma_f32 v22, -v18, v21, v20
	v_fmac_f32_e32 v21, v22, v19
	v_fma_f32 v18, -v18, v21, v20
	v_div_fmas_f32 v18, v18, v19, v21
	v_div_fixup_f32 v40, v18, v0, v177
	v_or_b32_e32 v0, s2, v185
	v_lshlrev_b64 v[18:19], 11, v[0:1]
	v_lshl_add_u64 v[18:19], s[74:75], 0, v[18:19]
	v_lshl_add_u64 v[18:19], s[76:77], 1, v[18:19]
	v_mul_f32_e32 v0, v50, v40
	v_mul_f32_e32 v20, v51, v40
	v_lshl_add_u64 v[18:19], v[172:173], 1, v[18:19]
	s_mov_b64 s[2:3], 0xb200000
	v_lshl_add_u64 v[22:23], v[18:19], 0, s[2:3]
	v_lshl_add_u64 v[22:23], v[172:173], 1, v[22:23]
	s_waitcnt vmcnt(17)
	v_mul_f32_e32 v0, v50, v40
	v_mul_f32_e32 v20, v51, v40
	v_mul_f32_e32 v0, v94, v0
	v_mul_f32_e32 v20, v95, v20
	v_cvt_pk_bf16_f32 v66, v0, v20
	v_mul_f32_e32 v0, v52, v40
	v_mul_f32_e32 v20, v53, v40
	v_mul_f32_e32 v0, v96, v0
	v_mul_f32_e32 v20, v97, v20
	v_cvt_pk_bf16_f32 v67, v0, v20
	v_mul_f32_e32 v0, v54, v40
	v_mul_f32_e32 v20, v55, v40
	v_mul_f32_e32 v0, v90, v0
	v_mul_f32_e32 v20, v91, v20
	v_cvt_pk_bf16_f32 v68, v0, v20
	v_mul_f32_e32 v0, v56, v40
	v_mul_f32_e32 v20, v57, v40
	v_mul_f32_e32 v0, v92, v0
	v_mul_f32_e32 v20, v93, v20
	v_cvt_pk_bf16_f32 v69, v0, v20
	s_nop 1
	v_permlane32_swap_b32_e32 v66, v68
	v_permlane32_swap_b32_e32 v67, v69
	s_nop 1
	global_store_dwordx4 v[22:23], v[66:69], off offset:0
	s_waitcnt vmcnt(16)
	v_mul_f32_e32 v0, v58, v40
	v_mul_f32_e32 v20, v59, v40
	v_mul_f32_e32 v0, v86, v0
	v_mul_f32_e32 v20, v87, v20
	v_cvt_pk_bf16_f32 v70, v0, v20
	v_mul_f32_e32 v0, v60, v40
	v_mul_f32_e32 v20, v61, v40
	v_mul_f32_e32 v0, v88, v0
	v_mul_f32_e32 v20, v89, v20
	v_cvt_pk_bf16_f32 v71, v0, v20
	v_mul_f32_e32 v0, v62, v40
	v_mul_f32_e32 v20, v63, v40
	v_mul_f32_e32 v0, v82, v0
	v_mul_f32_e32 v20, v83, v20
	v_cvt_pk_bf16_f32 v72, v0, v20
	v_mul_f32_e32 v0, v64, v40
	v_mul_f32_e32 v20, v65, v40
	v_mul_f32_e32 v0, v84, v0
	v_mul_f32_e32 v20, v85, v20
	v_cvt_pk_bf16_f32 v73, v0, v20
	s_nop 1
	v_permlane32_swap_b32_e32 v70, v72
	v_permlane32_swap_b32_e32 v71, v73
	s_nop 1
	global_store_dwordx4 v[22:23], v[70:73], off offset:32
	s_waitcnt vmcnt(15)
	v_mul_f32_e32 v0, v34, v40
	v_mul_f32_e32 v20, v35, v40
	v_mul_f32_e32 v0, v14, v0
	v_mul_f32_e32 v20, v15, v20
	v_cvt_pk_bf16_f32 v74, v0, v20
	v_mul_f32_e32 v0, v36, v40
	v_mul_f32_e32 v20, v37, v40
	v_mul_f32_e32 v0, v16, v0
	v_mul_f32_e32 v20, v17, v20
	v_cvt_pk_bf16_f32 v75, v0, v20
	v_mul_f32_e32 v0, v38, v40
	v_mul_f32_e32 v20, v39, v40
	v_mul_f32_e32 v0, v10, v0
	v_mul_f32_e32 v20, v11, v20
	v_cvt_pk_bf16_f32 v76, v0, v20
	v_mul_f32_e32 v0, v24, v40
	v_mul_f32_e32 v20, v25, v40
	v_mul_f32_e32 v0, v12, v0
	v_mul_f32_e32 v20, v13, v20
	v_cvt_pk_bf16_f32 v77, v0, v20
	s_nop 1
	v_permlane32_swap_b32_e32 v74, v76
	v_permlane32_swap_b32_e32 v75, v77
	s_nop 1
	global_store_dwordx4 v[22:23], v[74:77], off offset:64
	s_waitcnt vmcnt(14)
	v_mul_f32_e32 v0, v26, v40
	v_mul_f32_e32 v20, v27, v40
	v_mul_f32_e32 v0, v6, v0
	v_mul_f32_e32 v20, v7, v20
	v_cvt_pk_bf16_f32 v78, v0, v20
	v_mul_f32_e32 v0, v28, v40
	v_mul_f32_e32 v20, v29, v40
	v_mul_f32_e32 v0, v8, v0
	v_mul_f32_e32 v20, v9, v20
	v_cvt_pk_bf16_f32 v79, v0, v20
	v_mul_f32_e32 v0, v30, v40
	v_mul_f32_e32 v20, v31, v40
	v_mul_f32_e32 v0, v2, v0
	v_mul_f32_e32 v20, v3, v20
	v_cvt_pk_bf16_f32 v80, v0, v20
	v_mul_f32_e32 v0, v32, v40
	v_mul_f32_e32 v20, v33, v40
	v_mul_f32_e32 v0, v4, v0
	v_mul_f32_e32 v20, v5, v20
	v_cvt_pk_bf16_f32 v81, v0, v20
	s_nop 1
	v_permlane32_swap_b32_e32 v78, v80
	v_permlane32_swap_b32_e32 v79, v81
	s_nop 1
	global_store_dwordx4 v[22:23], v[78:81], off offset:96
	s_mov_b32 s2, s4
	s_mov_b32 s3, s5
	s_mov_b32 s76, s55
	v_mov_b32_e32 v0, v146
	v_mov_b32_e32 v2, v148
	v_mov_b32_e32 v3, v149
	v_mov_b32_e32 v4, v150
	v_mov_b32_e32 v8, v154
	v_mov_b32_e32 v9, v155
	v_mov_b32_e32 v19, v156
	v_mov_b32_e32 v20, v157
	s_waitcnt vmcnt(13)
	s_branch .Lpipe_part2

.LBB0_351:
	s_add_u32 s2, s78, s8
	s_addc_u32 s3, s79, s9
	v_ashrrev_i32_e32 v173, 31, v172
	v_lshl_add_u64 v[2:3], v[172:173], 2, s[2:3]
	v_mov_b32_e32 v0, v175
	global_load_dwordx4 v[94:97], v[2:3], off
	global_load_dwordx4 v[90:93], v[2:3], off offset:32
	global_load_dwordx4 v[86:89], v[2:3], off offset:64
	global_load_dwordx4 v[82:85], v[2:3], off offset:96
	global_load_dwordx4 v[14:17], v[2:3], off offset:128
	global_load_dwordx4 v[10:13], v[2:3], off offset:160
	global_load_dwordx4 v[6:9], v[2:3], off offset:192
	s_nop 0
	global_load_dwordx4 v[2:5], v[2:3], off offset:224
	s_ashr_i32 s77, s76, 31
	v_permlane32_swap_b32_e32 v175, v0
	s_nop 0
	v_add_f32_e32 v0, v175, v0
	v_div_scale_f32 v98, s[2:3], v0, v0, 1.0
	v_rcp_f32_e32 v99, v98
	s_nop 0
	v_fma_f32 v100, -v98, v99, 1.0
	v_fmac_f32_e32 v99, v100, v99
	v_div_scale_f32 v100, vcc, 1.0, v0, 1.0
	v_mul_f32_e32 v101, v100, v99
	v_fma_f32 v102, -v98, v101, v100
	v_fmac_f32_e32 v101, v102, v99
	v_fma_f32 v98, -v98, v101, v100
	v_div_fmas_f32 v98, v98, v99, v101
	v_div_fixup_f32 v0, v98, v0, 1.0
	v_mov_b32_e32 v98, v174
	s_nop 1
	v_permlane32_swap_b32_e32 v174, v98
	s_nop 0
	v_add_f32_e32 v98, v174, v98
	v_div_scale_f32 v99, s[2:3], v98, v98, 1.0
	v_rcp_f32_e32 v100, v99
	s_mov_b32 s2, 0xf800000
	v_fma_f32 v101, -v99, v100, 1.0
	v_fmac_f32_e32 v100, v101, v100
	v_div_scale_f32 v101, vcc, 1.0, v98, 1.0
	v_mul_f32_e32 v102, v101, v100
	v_fma_f32 v103, -v99, v102, v101
	v_fmac_f32_e32 v102, v103, v100
	v_fma_f32 v99, -v99, v102, v101
	v_div_fmas_f32 v99, v99, v100, v102
	v_div_fixup_f32 v98, v99, v98, 1.0
	v_mul_f32_e32 v98, v183, v98
	v_mul_f32_e32 v66, v66, v98
	v_fma_f32 v50, v50, v0, -v66
	v_mul_f32_e32 v66, v67, v98
	v_fma_f32 v51, v51, v0, -v66
	v_mul_f32_e32 v66, v51, v51
	v_mul_f32_e32 v67, v68, v98
	v_fmac_f32_e32 v66, v50, v50
	v_fma_f32 v52, v52, v0, -v67
	v_mul_f32_e32 v67, v69, v98
	v_fmac_f32_e32 v66, v52, v52
	v_fma_f32 v53, v53, v0, -v67
	v_mul_f32_e32 v67, v70, v98
	v_fmac_f32_e32 v66, v53, v53
	v_fma_f32 v54, v54, v0, -v67
	v_mul_f32_e32 v67, v71, v98
	v_fmac_f32_e32 v66, v54, v54
	v_fma_f32 v55, v55, v0, -v67
	v_mul_f32_e32 v67, v72, v98
	v_fmac_f32_e32 v66, v55, v55
	v_fma_f32 v56, v56, v0, -v67
	v_mul_f32_e32 v67, v73, v98
	v_fmac_f32_e32 v66, v56, v56
	v_fma_f32 v57, v57, v0, -v67
	v_mul_f32_e32 v67, v74, v98
	v_fmac_f32_e32 v66, v57, v57
	v_fma_f32 v58, v58, v0, -v67
	v_mul_f32_e32 v67, v75, v98
	v_fmac_f32_e32 v66, v58, v58
	v_fma_f32 v59, v59, v0, -v67
	v_mul_f32_e32 v67, v76, v98
	v_fmac_f32_e32 v66, v59, v59
	v_fma_f32 v60, v60, v0, -v67
	v_mul_f32_e32 v67, v77, v98
	v_fmac_f32_e32 v66, v60, v60
	v_fma_f32 v61, v61, v0, -v67
	v_mul_f32_e32 v67, v78, v98
	v_fmac_f32_e32 v66, v61, v61
	v_fma_f32 v62, v62, v0, -v67
	v_mul_f32_e32 v67, v79, v98
	v_fmac_f32_e32 v66, v62, v62
	v_fma_f32 v63, v63, v0, -v67
	v_mul_f32_e32 v67, v80, v98
	v_fmac_f32_e32 v66, v63, v63
	v_fma_f32 v64, v64, v0, -v67
	v_mul_f32_e32 v67, v81, v98
	v_fmac_f32_e32 v66, v64, v64
	v_fma_f32 v65, v65, v0, -v67
	v_mul_f32_e32 v34, v34, v98
	v_fmac_f32_e32 v66, v65, v65
	v_fma_f32 v34, v18, v0, -v34
	v_mul_f32_e32 v18, v35, v98
	v_fmac_f32_e32 v66, v34, v34
	v_fma_f32 v35, v19, v0, -v18
	v_mul_f32_e32 v18, v36, v98
	v_fmac_f32_e32 v66, v35, v35
	v_fma_f32 v36, v20, v0, -v18
	v_mul_f32_e32 v18, v37, v98
	v_fmac_f32_e32 v66, v36, v36
	v_fma_f32 v37, v21, v0, -v18
	v_mul_f32_e32 v18, v38, v98
	v_fmac_f32_e32 v66, v37, v37
	v_fma_f32 v38, v22, v0, -v18
	v_mul_f32_e32 v18, v39, v98
	v_fmac_f32_e32 v66, v38, v38
	v_fma_f32 v39, v23, v0, -v18
	v_mul_f32_e32 v18, v40, v98
	v_fmac_f32_e32 v66, v39, v39
	v_fma_f32 v24, v24, v0, -v18
	v_mul_f32_e32 v18, v41, v98
	v_fmac_f32_e32 v66, v24, v24
	v_fma_f32 v25, v25, v0, -v18
	v_mul_f32_e32 v18, v42, v98
	v_fmac_f32_e32 v66, v25, v25
	v_fma_f32 v26, v26, v0, -v18
	v_mul_f32_e32 v18, v43, v98
	v_fmac_f32_e32 v66, v26, v26
	v_fma_f32 v27, v27, v0, -v18
	v_mul_f32_e32 v18, v44, v98
	v_fmac_f32_e32 v66, v27, v27
	v_fma_f32 v28, v28, v0, -v18
	v_mul_f32_e32 v18, v45, v98
	v_fmac_f32_e32 v66, v28, v28
	v_fma_f32 v29, v29, v0, -v18
	v_mul_f32_e32 v18, v46, v98
	v_fmac_f32_e32 v66, v29, v29
	v_fma_f32 v30, v30, v0, -v18
	v_mul_f32_e32 v18, v47, v98
	v_fmac_f32_e32 v66, v30, v30
	v_fma_f32 v31, v31, v0, -v18
	v_mul_f32_e32 v18, v48, v98
	v_fmac_f32_e32 v66, v31, v31
	v_fma_f32 v32, v32, v0, -v18
	v_mul_f32_e32 v18, v49, v98
	v_fmac_f32_e32 v66, v32, v32
	v_fma_f32 v33, v33, v0, -v18
	v_fmac_f32_e32 v66, v33, v33
	v_mov_b32_e32 v0, v66
	s_nop 1
	v_permlane32_swap_b32_e32 v66, v0
	s_nop 0
	v_add_f32_e32 v0, v66, v0
	v_fmamk_f32 v0, v0, 0x3c800000, v233
	v_cmp_gt_f32_e32 vcc, s2, v0
	v_mul_f32_e32 v18, 0x4f800000, v0
	s_nop 0
	v_cndmask_b32_e32 v0, v0, v18, vcc
	v_sqrt_f32_e32 v18, v0
	s_nop 0
	v_add_u32_e32 v19, -1, v18
	v_fma_f32 v20, -v19, v18, v0
	v_cmp_ge_f32_e64 s[2:3], 0, v20
	v_add_u32_e32 v20, 1, v18
	s_nop 0
	v_cndmask_b32_e64 v19, v18, v19, s[2:3]
	v_fma_f32 v18, -v20, v18, v0
	v_cmp_lt_f32_e64 s[2:3], 0, v18
	s_nop 1
	v_cndmask_b32_e64 v18, v19, v20, s[2:3]
	v_mul_f32_e32 v19, 0x37800000, v18
	v_cndmask_b32_e32 v18, v18, v19, vcc
	v_cmp_class_f32_e32 vcc, v0, v232
	s_nop 1
	v_cndmask_b32_e32 v0, v18, v0, vcc
	v_div_scale_f32 v18, s[2:3], v0, v0, v177
	v_rcp_f32_e32 v19, v18
	v_readlane_b32 s2, v244, 1
	s_add_i32 s2, s2, s68
	v_fma_f32 v20, -v18, v19, 1.0
	v_fmac_f32_e32 v19, v20, v19
	v_div_scale_f32 v20, vcc, v177, v0, v177
	v_mul_f32_e32 v21, v20, v19
	v_fma_f32 v22, -v18, v21, v20
	v_fmac_f32_e32 v21, v22, v19
	v_fma_f32 v18, -v18, v21, v20
	v_div_fmas_f32 v18, v18, v19, v21
	v_div_fixup_f32 v40, v18, v0, v177
	v_or_b32_e32 v0, s2, v185
	v_lshlrev_b64 v[18:19], 11, v[0:1]
	v_lshl_add_u64 v[18:19], s[74:75], 0, v[18:19]
	v_lshl_add_u64 v[18:19], s[76:77], 1, v[18:19]
	v_mul_f32_e32 v0, v50, v40
	v_mul_f32_e32 v20, v51, v40
	v_lshl_add_u64 v[18:19], v[172:173], 1, v[18:19]
	s_mov_b64 s[2:3], 0xb200000
	v_lshl_add_u64 v[22:23], v[18:19], 0, s[2:3]
	v_lshl_add_u64 v[22:23], v[172:173], 1, v[22:23]
	s_waitcnt vmcnt(6)
	v_mul_f32_e32 v0, v50, v40
	v_mul_f32_e32 v20, v51, v40
	v_mul_f32_e32 v0, v94, v0
	v_mul_f32_e32 v20, v95, v20
	v_cvt_pk_bf16_f32 v66, v0, v20
	v_mul_f32_e32 v0, v52, v40
	v_mul_f32_e32 v20, v53, v40
	v_mul_f32_e32 v0, v96, v0
	v_mul_f32_e32 v20, v97, v20
	v_cvt_pk_bf16_f32 v67, v0, v20
	v_mul_f32_e32 v0, v54, v40
	v_mul_f32_e32 v20, v55, v40
	v_mul_f32_e32 v0, v90, v0
	v_mul_f32_e32 v20, v91, v20
	v_cvt_pk_bf16_f32 v68, v0, v20
	v_mul_f32_e32 v0, v56, v40
	v_mul_f32_e32 v20, v57, v40
	v_mul_f32_e32 v0, v92, v0
	v_mul_f32_e32 v20, v93, v20
	v_cvt_pk_bf16_f32 v69, v0, v20
	s_nop 1
	v_permlane32_swap_b32_e32 v66, v68
	v_permlane32_swap_b32_e32 v67, v69
	s_nop 1
	global_store_dwordx4 v[22:23], v[66:69], off offset:0
	s_waitcnt vmcnt(5)
	v_mul_f32_e32 v0, v58, v40
	v_mul_f32_e32 v20, v59, v40
	v_mul_f32_e32 v0, v86, v0
	v_mul_f32_e32 v20, v87, v20
	v_cvt_pk_bf16_f32 v70, v0, v20
	v_mul_f32_e32 v0, v60, v40
	v_mul_f32_e32 v20, v61, v40
	v_mul_f32_e32 v0, v88, v0
	v_mul_f32_e32 v20, v89, v20
	v_cvt_pk_bf16_f32 v71, v0, v20
	v_mul_f32_e32 v0, v62, v40
	v_mul_f32_e32 v20, v63, v40
	v_mul_f32_e32 v0, v82, v0
	v_mul_f32_e32 v20, v83, v20
	v_cvt_pk_bf16_f32 v72, v0, v20
	v_mul_f32_e32 v0, v64, v40
	v_mul_f32_e32 v20, v65, v40
	v_mul_f32_e32 v0, v84, v0
	v_mul_f32_e32 v20, v85, v20
	v_cvt_pk_bf16_f32 v73, v0, v20
	s_nop 1
	v_permlane32_swap_b32_e32 v70, v72
	v_permlane32_swap_b32_e32 v71, v73
	s_nop 1
	global_store_dwordx4 v[22:23], v[70:73], off offset:32
	s_waitcnt vmcnt(4)
	v_mul_f32_e32 v0, v34, v40
	v_mul_f32_e32 v20, v35, v40
	v_mul_f32_e32 v0, v14, v0
	v_mul_f32_e32 v20, v15, v20
	v_cvt_pk_bf16_f32 v74, v0, v20
	v_mul_f32_e32 v0, v36, v40
	v_mul_f32_e32 v20, v37, v40
	v_mul_f32_e32 v0, v16, v0
	v_mul_f32_e32 v20, v17, v20
	v_cvt_pk_bf16_f32 v75, v0, v20
	v_mul_f32_e32 v0, v38, v40
	v_mul_f32_e32 v20, v39, v40
	v_mul_f32_e32 v0, v10, v0
	v_mul_f32_e32 v20, v11, v20
	v_cvt_pk_bf16_f32 v76, v0, v20
	v_mul_f32_e32 v0, v24, v40
	v_mul_f32_e32 v20, v25, v40
	v_mul_f32_e32 v0, v12, v0
	v_mul_f32_e32 v20, v13, v20
	v_cvt_pk_bf16_f32 v77, v0, v20
	s_nop 1
	v_permlane32_swap_b32_e32 v74, v76
	v_permlane32_swap_b32_e32 v75, v77
	s_nop 1
	global_store_dwordx4 v[22:23], v[74:77], off offset:64
	s_waitcnt vmcnt(3)
	v_mul_f32_e32 v0, v26, v40
	v_mul_f32_e32 v20, v27, v40
	v_mul_f32_e32 v0, v6, v0
	v_mul_f32_e32 v20, v7, v20
	v_cvt_pk_bf16_f32 v78, v0, v20
	v_mul_f32_e32 v0, v28, v40
	v_mul_f32_e32 v20, v29, v40
	v_mul_f32_e32 v0, v8, v0
	v_mul_f32_e32 v20, v9, v20
	v_cvt_pk_bf16_f32 v79, v0, v20
	v_mul_f32_e32 v0, v30, v40
	v_mul_f32_e32 v20, v31, v40
	v_mul_f32_e32 v0, v2, v0
	v_mul_f32_e32 v20, v3, v20
	v_cvt_pk_bf16_f32 v80, v0, v20
	v_mul_f32_e32 v0, v32, v40
	v_mul_f32_e32 v20, v33, v40
	v_mul_f32_e32 v0, v4, v0
	v_mul_f32_e32 v20, v5, v20
	v_cvt_pk_bf16_f32 v81, v0, v20
	s_nop 1
	v_permlane32_swap_b32_e32 v78, v80
	v_permlane32_swap_b32_e32 v79, v81
	s_nop 1
	global_store_dwordx4 v[22:23], v[78:81], off offset:96
	s_barrier
	s_mov_b64 s[2:3], 0
